# GEMM K-loop back-edge rotation (7.11): counter/pointer SALU block moved from after the loop-back barrier into the gaps of the last MFMA block
# speedup vs baseline: 1.0028x; 1.0028x over previous
; #define PG8_STAGE(bufoff, gbase, voff) do { _Pragma("unroll") for (int _i = 0; _i < 2; ++_i) \
;         __builtin_amdgcn_global_load_lds((const unsigned*)((const char*)(gbase) + (voff)[_i]), (PG8_LAS unsigned*)(lds + (bufoff) + ldsw + _i * 8192), 16, 0, 0); } while (0)
; #define PG8_LDA(dst, b, h) do { _Pragma("unroll") for (int m = 0; m < 4; ++m) _Pragma("unroll") for (int k = 0; k < 2; ++k) dst[m][k] = *(const PG8_LAS bf16x8*)(lds + PG8_SA(b, h) + aoff + m * 2048 + k * 1024); } while (0)
; #define PG8_LDB(dst, b, h) do { _Pragma("unroll") for (int n = 0; n < 2; ++n) _Pragma("unroll") for (int k = 0; k < 2; ++k) dst[n][k] = *(const PG8_LAS bf16x8*)(lds + PG8_SB(b, h) + boff + n * 2048 + k * 1024); } while (0)
; #define PG8_MMA(ai, bj, At, Bt) do { __builtin_amdgcn_s_setprio(1); _Pragma("unroll") for (int m = 0; m < 4; ++m) _Pragma("unroll") for (int n = 0; n < 2; ++n) _Pragma("unroll") for (int k = 0; k < 2; ++k) \
;         acc[ai][bj][m][n] = __builtin_amdgcn_mfma_f32_16x16x32_bf16(Bt[n][k], At[m][k], acc[ai][bj][m][n], 0, 0, 0); __builtin_amdgcn_s_setprio(0); } while (0)
; #define PG8_WAIT_V(n) asm volatile("s_waitcnt vmcnt(" #n ")" ::: "memory")
; template <class Epi, class Sched, bool ALIGN_EPI = false, bool SP2 = false>
; __device__ __forceinline__ void gemm_phase(PG8_LAS unsigned char* lds, const Gemm g, const Sched& S, const Epi& E, const int tid_in) {
;     ...
;         for (int t = 0; t < nt; t += 2) {
;             const bool last = (t == nt - 2);
;             const char* a1 = cA + (size_t)(t + 1) * kstep;
;             const char* a2 = last ? nA : cA + (size_t)(t + 2) * kstep; const char* b2 = last ? nB : cB + (size_t)(t + 2) * kstep;
;             const char* a3 = a2 + kstep; const char* b3 = b2 + kstep;
;             if (last && has_next) S.a_ready(nxt);
;             if constexpr (SP2) {
;             PG8_LDB(B0, 0, 0); PG8_LDB(B1, 0, 1); PG8_SCHED; PG8_LDA(At, 0, 0); PG8_STAGE(PG8_SA(1, 1), a1 + hstepA, voffA);
;             PG8_WAIT_V(8); PG8_WAIT_L(0); PG8_BAR; PG8_MMA(0, 0, At, B0); PG8_MMA(0, 1, At, B1); PG8_BAR; PG8_SCHED;
;     ...
; #pragma unroll
;         for (int a = 0; a < 2; ++a)
; #pragma unroll
;             for (int b = 0; b < 2; ++b)
; #pragma unroll
;                 for (int m = 0; m < 4; ++m)
; #pragma unroll
;                     for (int n = 0; n < 2; ++n) acc[a][b][m][n] = (f32x4){0.f, 0.f, 0.f, 0.f};
.LBB0_225:
	s_add_u32 vcc_lo, s48, 0x100
	s_addc_u32 vcc_hi, s49, 0
	s_add_u32 s46, s50, 0x80
	v_mov_b32_e32 v2, 0
	s_addc_u32 s47, s51, 0
	s_mov_b32 s48, 0
	v_mov_b32_e32 v3, v2
	v_mov_b32_e32 v4, v2
	v_mov_b32_e32 v5, v2
	v_mov_b32_e32 v6, v2
	v_mov_b32_e32 v7, v2
	v_mov_b32_e32 v8, v2
	v_mov_b32_e32 v9, v2
	v_mov_b32_e32 v18, v2
	v_mov_b32_e32 v19, v2
	v_mov_b32_e32 v20, v2
	v_mov_b32_e32 v21, v2
	v_mov_b32_e32 v22, v2
	v_mov_b32_e32 v23, v2
	v_mov_b32_e32 v24, v2
	v_mov_b32_e32 v25, v2
	v_mov_b32_e32 v34, v2
	v_mov_b32_e32 v35, v2
	v_mov_b32_e32 v36, v2
	v_mov_b32_e32 v37, v2
	v_mov_b32_e32 v38, v2
	v_mov_b32_e32 v39, v2
	v_mov_b32_e32 v40, v2
	v_mov_b32_e32 v41, v2
	v_mov_b32_e32 v50, v2
	v_mov_b32_e32 v51, v2
	v_mov_b32_e32 v52, v2
	v_mov_b32_e32 v53, v2
	v_mov_b32_e32 v54, v2
	v_mov_b32_e32 v55, v2
	v_mov_b32_e32 v56, v2
	v_mov_b32_e32 v57, v2
	v_mov_b32_e32 v10, v2
	v_mov_b32_e32 v11, v2
	v_mov_b32_e32 v12, v2
	v_mov_b32_e32 v13, v2
	v_mov_b32_e32 v14, v2
	v_mov_b32_e32 v15, v2
	v_mov_b32_e32 v16, v2
	v_mov_b32_e32 v17, v2
	v_mov_b32_e32 v26, v2
	v_mov_b32_e32 v27, v2
	v_mov_b32_e32 v28, v2
	v_mov_b32_e32 v29, v2
	v_mov_b32_e32 v30, v2
	v_mov_b32_e32 v31, v2
	v_mov_b32_e32 v32, v2
	v_mov_b32_e32 v33, v2
	v_mov_b32_e32 v42, v2
	v_mov_b32_e32 v43, v2
	v_mov_b32_e32 v44, v2
	v_mov_b32_e32 v45, v2
	v_mov_b32_e32 v46, v2
	v_mov_b32_e32 v47, v2
	v_mov_b32_e32 v48, v2
	v_mov_b32_e32 v49, v2
	v_mov_b32_e32 v58, v2
	v_mov_b32_e32 v59, v2
	v_mov_b32_e32 v60, v2
	v_mov_b32_e32 v61, v2
	v_mov_b32_e32 v62, v2
	v_mov_b32_e32 v63, v2
	v_mov_b32_e32 v64, v2
	v_mov_b32_e32 v65, v2
	v_mov_b32_e32 v66, v2
	v_mov_b32_e32 v67, v2
	v_mov_b32_e32 v68, v2
	v_mov_b32_e32 v69, v2
	v_mov_b32_e32 v70, v2
	v_mov_b32_e32 v71, v2
	v_mov_b32_e32 v72, v2
	v_mov_b32_e32 v73, v2
	v_mov_b32_e32 v82, v2
	v_mov_b32_e32 v83, v2
	v_mov_b32_e32 v84, v2
	v_mov_b32_e32 v85, v2
	v_mov_b32_e32 v86, v2
	v_mov_b32_e32 v87, v2
	v_mov_b32_e32 v88, v2
	v_mov_b32_e32 v89, v2
	v_mov_b32_e32 v98, v2
	v_mov_b32_e32 v99, v2
	v_mov_b32_e32 v100, v2
	v_mov_b32_e32 v101, v2
	v_mov_b32_e32 v102, v2
	v_mov_b32_e32 v103, v2
	v_mov_b32_e32 v104, v2
	v_mov_b32_e32 v105, v2
	v_mov_b32_e32 v114, v2
	v_mov_b32_e32 v115, v2
	v_mov_b32_e32 v116, v2
	v_mov_b32_e32 v117, v2
	v_mov_b32_e32 v118, v2
	v_mov_b32_e32 v119, v2
	v_mov_b32_e32 v120, v2
	v_mov_b32_e32 v121, v2
	v_mov_b32_e32 v74, v2
	v_mov_b32_e32 v75, v2
	v_mov_b32_e32 v76, v2
	v_mov_b32_e32 v77, v2
	v_mov_b32_e32 v78, v2
	v_mov_b32_e32 v79, v2
	v_mov_b32_e32 v80, v2
	v_mov_b32_e32 v81, v2
	v_mov_b32_e32 v90, v2
	v_mov_b32_e32 v91, v2
	v_mov_b32_e32 v92, v2
	v_mov_b32_e32 v93, v2
	v_mov_b32_e32 v94, v2
	v_mov_b32_e32 v95, v2
	v_mov_b32_e32 v96, v2
	v_mov_b32_e32 v97, v2
	v_mov_b32_e32 v106, v2
	v_mov_b32_e32 v107, v2
	v_mov_b32_e32 v108, v2
	v_mov_b32_e32 v109, v2
	v_mov_b32_e32 v110, v2
	v_mov_b32_e32 v111, v2
	v_mov_b32_e32 v112, v2
	v_mov_b32_e32 v113, v2
	v_mov_b32_e32 v122, v2
	v_mov_b32_e32 v123, v2
	v_mov_b32_e32 v124, v2
	v_mov_b32_e32 v125, v2
	v_mov_b32_e32 v126, v2
	v_mov_b32_e32 v127, v2
	v_mov_b32_e32 v128, v2
	v_mov_b32_e32 v129, v2
	s_add_i32 s50, s48, 2
	s_add_u32 s51, s46, 0x80
	s_addc_u32 s49, s47, 0
	s_add_i32 s26, 0, 0x10000
	s_cmp_eq_u32 s9, s48
	s_cselect_b32 s49, s83, s49
	s_cselect_b32 s48, s82, s51
	s_cselect_b32 s61, s85, vcc_hi
	s_cselect_b32 s60, s84, vcc_lo
	s_add_i32 s51, 0, 0x14000
.LBB0_226:
	v_add_u32_e32 v142, s26, v252
	v_add_u32_e32 v158, s51, v252
	ds_read_b128 v[130:133], v142
	ds_read_b128 v[134:137], v142 offset:1024
	ds_read_b128 v[138:141], v142 offset:2048
	ds_read_b128 v[142:145], v142 offset:3072
	ds_read_b128 v[146:149], v158
	ds_read_b128 v[150:153], v158 offset:1024
	ds_read_b128 v[154:157], v158 offset:2048
	ds_read_b128 v[158:161], v158 offset:3072
	v_lshl_add_u64 v[194:195], s[46:47], 0, v[222:223]
	s_add_i32 m0, s17, 0xc000
	ds_read_b128 v[162:165], v244
	ds_read_b128 v[166:169], v244 offset:1024
	ds_read_b128 v[170:173], v244 offset:2048
	ds_read_b128 v[174:177], v244 offset:3072
	ds_read_b128 v[178:181], v244 offset:4096
	ds_read_b128 v[182:185], v244 offset:5120
	ds_read_b128 v[186:189], v244 offset:6144
	ds_read_b128 v[190:193], v244 offset:7168
	global_load_lds_dwordx4 v[194:195], off
	v_lshl_add_u64 v[194:195], s[46:47], 0, v[220:221]
	s_add_i32 m0, s17, 0xe000
	s_nop 0
	global_load_lds_dwordx4 v[194:195], off
	s_waitcnt vmcnt(8)
	s_waitcnt lgkmcnt(0)
	s_barrier
	s_setprio 1
	s_waitcnt lgkmcnt(0)
	v_mfma_f32_16x16x32_bf16 v[126:129], v[130:133], v[162:165], v[126:129]
	v_mfma_f32_16x16x32_bf16 v[122:125], v[138:141], v[162:165], v[122:125]
	v_mfma_f32_16x16x32_bf16 v[110:113], v[130:133], v[170:173], v[110:113]
	v_mfma_f32_16x16x32_bf16 v[106:109], v[138:141], v[170:173], v[106:109]
	v_mfma_f32_16x16x32_bf16 v[94:97], v[130:133], v[178:181], v[94:97]
	v_mfma_f32_16x16x32_bf16 v[90:93], v[138:141], v[178:181], v[90:93]
	v_mfma_f32_16x16x32_bf16 v[78:81], v[130:133], v[186:189], v[78:81]
	v_mfma_f32_16x16x32_bf16 v[74:77], v[138:141], v[186:189], v[74:77]
	v_mfma_f32_16x16x32_bf16 v[126:129], v[134:137], v[166:169], v[126:129]
	v_mfma_f32_16x16x32_bf16 v[122:125], v[142:145], v[166:169], v[122:125]
	v_mfma_f32_16x16x32_bf16 v[110:113], v[134:137], v[174:177], v[110:113]
	v_mfma_f32_16x16x32_bf16 v[106:109], v[142:145], v[174:177], v[106:109]
	v_mfma_f32_16x16x32_bf16 v[94:97], v[134:137], v[182:185], v[94:97]
	v_mfma_f32_16x16x32_bf16 v[90:93], v[142:145], v[182:185], v[90:93]
	v_mfma_f32_16x16x32_bf16 v[78:81], v[134:137], v[190:193], v[78:81]
	v_mfma_f32_16x16x32_bf16 v[74:77], v[142:145], v[190:193], v[74:77]
	s_setprio 0
	s_setprio 1
	v_mfma_f32_16x16x32_bf16 v[118:121], v[146:149], v[162:165], v[118:121]
	v_mfma_f32_16x16x32_bf16 v[114:117], v[154:157], v[162:165], v[114:117]
	v_mfma_f32_16x16x32_bf16 v[102:105], v[146:149], v[170:173], v[102:105]
	v_mfma_f32_16x16x32_bf16 v[98:101], v[154:157], v[170:173], v[98:101]
	v_mfma_f32_16x16x32_bf16 v[86:89], v[146:149], v[178:181], v[86:89]
	v_mfma_f32_16x16x32_bf16 v[82:85], v[154:157], v[178:181], v[82:85]
	v_mfma_f32_16x16x32_bf16 v[70:73], v[146:149], v[186:189], v[70:73]
	v_mfma_f32_16x16x32_bf16 v[66:69], v[154:157], v[186:189], v[66:69]
	v_mfma_f32_16x16x32_bf16 v[118:121], v[150:153], v[166:169], v[118:121]
	v_mfma_f32_16x16x32_bf16 v[114:117], v[158:161], v[166:169], v[114:117]
	v_mfma_f32_16x16x32_bf16 v[102:105], v[150:153], v[174:177], v[102:105]
	v_mfma_f32_16x16x32_bf16 v[98:101], v[158:161], v[174:177], v[98:101]
	v_mfma_f32_16x16x32_bf16 v[86:89], v[150:153], v[182:185], v[86:89]
	v_mfma_f32_16x16x32_bf16 v[82:85], v[158:161], v[182:185], v[82:85]
	v_mfma_f32_16x16x32_bf16 v[70:73], v[150:153], v[190:193], v[70:73]
	v_mfma_f32_16x16x32_bf16 v[66:69], v[158:161], v[190:193], v[66:69]
	s_setprio 0
	s_barrier
; #define PG8_STAGE(bufoff, gbase, voff) do { _Pragma("unroll") for (int _i = 0; _i < 2; ++_i) \
;         __builtin_amdgcn_global_load_lds((const unsigned*)((const char*)(gbase) + (voff)[_i]), (PG8_LAS unsigned*)(lds + (bufoff) + ldsw + _i * 8192), 16, 0, 0); } while (0)
; #define PG8_LDA(dst, b, h) do { _Pragma("unroll") for (int m = 0; m < 4; ++m) _Pragma("unroll") for (int k = 0; k < 2; ++k) dst[m][k] = *(const PG8_LAS bf16x8*)(lds + PG8_SA(b, h) + aoff + m * 2048 + k * 1024); } while (0)
; #define PG8_LDB(dst, b, h) do { _Pragma("unroll") for (int n = 0; n < 2; ++n) _Pragma("unroll") for (int k = 0; k < 2; ++k) dst[n][k] = *(const PG8_LAS bf16x8*)(lds + PG8_SB(b, h) + boff + n * 2048 + k * 1024); } while (0)
; #define PG8_MMA(ai, bj, At, Bt) do { __builtin_amdgcn_s_setprio(1); _Pragma("unroll") for (int m = 0; m < 4; ++m) _Pragma("unroll") for (int n = 0; n < 2; ++n) _Pragma("unroll") for (int k = 0; k < 2; ++k) \
;         acc[ai][bj][m][n] = __builtin_amdgcn_mfma_f32_16x16x32_bf16(Bt[n][k], At[m][k], acc[ai][bj][m][n], 0, 0, 0); __builtin_amdgcn_s_setprio(0); } while (0)
; #define PG8_WAIT_V(n) asm volatile("s_waitcnt vmcnt(" #n ")" ::: "memory")
; #define PG8_WAIT_L(n) asm volatile("s_waitcnt lgkmcnt(" #n ")" ::: "memory")
; #define PG8_BAR __builtin_amdgcn_s_barrier()
; #define PG8_SCHED __builtin_amdgcn_sched_barrier(0)
; template <class Epi, class Sched, bool ALIGN_EPI = false, bool SP2 = false>
; __device__ __forceinline__ void gemm_phase(PG8_LAS unsigned char* lds, const Gemm g, const Sched& S, const Epi& E, const int tid_in) {
;     ...
;             PG8_LDA(At, 0, 1); PG8_STAGE(PG8_SB(0, 0), b2, voffB); PG8_STAGE(PG8_SB(0, 1), b2 + hstep, voffB); PG8_STAGE(PG8_SA(0, 0), a2, voffA);
;             PG8_WAIT_V(8); PG8_WAIT_L(0); PG8_BAR; PG8_MMA(1, 0, At, B0); PG8_MMA(1, 1, At, B1); PG8_BAR; PG8_SCHED;
;             PG8_LDB(B0, 1, 0); PG8_LDB(B1, 1, 1); PG8_SCHED; PG8_LDA(At, 1, 0); PG8_STAGE(PG8_SA(0, 1), a2 + hstepA, voffA);
	s_add_i32 s26, s26, s16
	v_lshl_add_u64 v[194:195], s[60:61], 0, v[218:219]
	s_mov_b32 m0, s26
	ds_read_b128 v[162:165], v244 offset:16384
	ds_read_b128 v[166:169], v244 offset:17408
	ds_read_b128 v[170:173], v244 offset:18432
	ds_read_b128 v[174:177], v244 offset:19456
	ds_read_b128 v[178:181], v244 offset:20480
	ds_read_b128 v[182:185], v244 offset:21504
	ds_read_b128 v[186:189], v244 offset:22528
	ds_read_b128 v[190:193], v244 offset:23552
	global_load_lds_dwordx4 v[194:195], off
	s_add_i32 m0, s26, 0x2000
	v_lshl_add_u64 v[196:197], s[60:61], 0, v[214:215]
	s_add_u32 s60, s60, s96
	s_addc_u32 s61, s61, 0
	s_add_i32 s26, s51, s16
	global_load_lds_dwordx4 v[196:197], off
	v_lshl_add_u64 v[198:199], s[60:61], 0, v[218:219]
	s_mov_b32 m0, s26
	v_lshl_add_u64 v[200:201], s[60:61], 0, v[214:215]
	global_load_lds_dwordx4 v[198:199], off
	s_add_i32 m0, s26, 0x2000
	v_lshl_add_u64 v[202:203], s[48:49], 0, v[216:217]
	global_load_lds_dwordx4 v[200:201], off
	s_mov_b32 m0, s17
	v_lshl_add_u64 v[204:205], s[48:49], 0, v[212:213]
	global_load_lds_dwordx4 v[202:203], off
	s_mov_b32 m0, s25
	s_nop 0
	global_load_lds_dwordx4 v[204:205], off
	s_waitcnt vmcnt(8)
	s_waitcnt lgkmcnt(0)
	s_barrier
	s_setprio 1
	s_waitcnt lgkmcnt(0)
	v_mfma_f32_16x16x32_bf16 v[62:65], v[130:133], v[162:165], v[62:65]
	v_mfma_f32_16x16x32_bf16 v[58:61], v[138:141], v[162:165], v[58:61]
	v_mfma_f32_16x16x32_bf16 v[46:49], v[130:133], v[170:173], v[46:49]
	v_mfma_f32_16x16x32_bf16 v[42:45], v[138:141], v[170:173], v[42:45]
	v_mfma_f32_16x16x32_bf16 v[30:33], v[130:133], v[178:181], v[30:33]
	v_mfma_f32_16x16x32_bf16 v[26:29], v[138:141], v[178:181], v[26:29]
	v_mfma_f32_16x16x32_bf16 v[14:17], v[130:133], v[186:189], v[14:17]
	v_mfma_f32_16x16x32_bf16 v[10:13], v[138:141], v[186:189], v[10:13]
	v_mfma_f32_16x16x32_bf16 v[62:65], v[134:137], v[166:169], v[62:65]
	v_mfma_f32_16x16x32_bf16 v[58:61], v[142:145], v[166:169], v[58:61]
	v_mfma_f32_16x16x32_bf16 v[46:49], v[134:137], v[174:177], v[46:49]
	v_mfma_f32_16x16x32_bf16 v[42:45], v[142:145], v[174:177], v[42:45]
	v_mfma_f32_16x16x32_bf16 v[30:33], v[134:137], v[182:185], v[30:33]
	v_mfma_f32_16x16x32_bf16 v[26:29], v[142:145], v[182:185], v[26:29]
	v_mfma_f32_16x16x32_bf16 v[14:17], v[134:137], v[190:193], v[14:17]
	v_mfma_f32_16x16x32_bf16 v[10:13], v[142:145], v[190:193], v[10:13]
	s_setprio 0
	s_setprio 1
	v_mfma_f32_16x16x32_bf16 v[54:57], v[146:149], v[162:165], v[54:57]
	v_mfma_f32_16x16x32_bf16 v[50:53], v[154:157], v[162:165], v[50:53]
	v_mfma_f32_16x16x32_bf16 v[38:41], v[146:149], v[170:173], v[38:41]
	v_mfma_f32_16x16x32_bf16 v[34:37], v[154:157], v[170:173], v[34:37]
	v_mfma_f32_16x16x32_bf16 v[22:25], v[146:149], v[178:181], v[22:25]
	v_mfma_f32_16x16x32_bf16 v[18:21], v[154:157], v[178:181], v[18:21]
	v_mfma_f32_16x16x32_bf16 v[6:9], v[146:149], v[186:189], v[6:9]
	v_mfma_f32_16x16x32_bf16 v[2:5], v[154:157], v[186:189], v[2:5]
	v_mfma_f32_16x16x32_bf16 v[54:57], v[150:153], v[166:169], v[54:57]
	v_mfma_f32_16x16x32_bf16 v[50:53], v[158:161], v[166:169], v[50:53]
	v_mfma_f32_16x16x32_bf16 v[38:41], v[150:153], v[174:177], v[38:41]
	v_mfma_f32_16x16x32_bf16 v[34:37], v[158:161], v[174:177], v[34:37]
	v_mfma_f32_16x16x32_bf16 v[22:25], v[150:153], v[182:185], v[22:25]
	v_mfma_f32_16x16x32_bf16 v[18:21], v[158:161], v[182:185], v[18:21]
	v_mfma_f32_16x16x32_bf16 v[6:9], v[150:153], v[190:193], v[6:9]
	v_mfma_f32_16x16x32_bf16 v[2:5], v[158:161], v[190:193], v[2:5]
	s_setprio 0
	s_barrier
	s_add_i32 s26, 0, 0x18000
	s_add_i32 s51, 0, 0x1c000
	v_add_u32_e32 v142, s26, v252
	v_add_u32_e32 v158, s51, v252
	ds_read_b128 v[130:133], v142
	ds_read_b128 v[134:137], v142 offset:1024
	ds_read_b128 v[138:141], v142 offset:2048
	ds_read_b128 v[142:145], v142 offset:3072
	ds_read_b128 v[146:149], v158
	ds_read_b128 v[150:153], v158 offset:1024
	ds_read_b128 v[154:157], v158 offset:2048
	ds_read_b128 v[158:161], v158 offset:3072
	s_add_u32 s48, s48, s12
	s_addc_u32 s49, s49, 0
	s_mov_b32 m0, s57
	v_lshl_add_u64 v[224:225], s[48:49], 0, v[216:217]
	ds_read_b128 v[162:165], v244 offset:32768
	ds_read_b128 v[166:169], v244 offset:33792
	ds_read_b128 v[170:173], v244 offset:34816
	ds_read_b128 v[174:177], v244 offset:35840
	ds_read_b128 v[178:181], v244 offset:36864
	ds_read_b128 v[182:185], v244 offset:37888
	ds_read_b128 v[186:189], v244 offset:38912
	ds_read_b128 v[190:193], v244 offset:39936
	global_load_lds_dwordx4 v[224:225], off
	v_lshl_add_u64 v[224:225], s[48:49], 0, v[212:213]
	s_mov_b32 m0, s0
	s_nop 0
	global_load_lds_dwordx4 v[224:225], off
	s_waitcnt vmcnt(8)
	s_waitcnt lgkmcnt(0)
	s_barrier
; #define PG8_STAGE(bufoff, gbase, voff) do { _Pragma("unroll") for (int _i = 0; _i < 2; ++_i) \
;         __builtin_amdgcn_global_load_lds((const unsigned*)((const char*)(gbase) + (voff)[_i]), (PG8_LAS unsigned*)(lds + (bufoff) + ldsw + _i * 8192), 16, 0, 0); } while (0)
; #define PG8_LDA(dst, b, h) do { _Pragma("unroll") for (int m = 0; m < 4; ++m) _Pragma("unroll") for (int k = 0; k < 2; ++k) dst[m][k] = *(const PG8_LAS bf16x8*)(lds + PG8_SA(b, h) + aoff + m * 2048 + k * 1024); } while (0)
; #define PG8_MMA(ai, bj, At, Bt) do { __builtin_amdgcn_s_setprio(1); _Pragma("unroll") for (int m = 0; m < 4; ++m) _Pragma("unroll") for (int n = 0; n < 2; ++n) _Pragma("unroll") for (int k = 0; k < 2; ++k) \
;         acc[ai][bj][m][n] = __builtin_amdgcn_mfma_f32_16x16x32_bf16(Bt[n][k], At[m][k], acc[ai][bj][m][n], 0, 0, 0); __builtin_amdgcn_s_setprio(0); } while (0)
; #define PG8_WAIT_V(n) asm volatile("s_waitcnt vmcnt(" #n ")" ::: "memory")
; #define PG8_WAIT_L(n) asm volatile("s_waitcnt lgkmcnt(" #n ")" ::: "memory")
; #define PG8_BAR __builtin_amdgcn_s_barrier()
; #define PG8_SCHED __builtin_amdgcn_sched_barrier(0)
; template <class Epi, class Sched, bool ALIGN_EPI = false, bool SP2 = false>
; __device__ __forceinline__ void gemm_phase(PG8_LAS unsigned char* lds, const Gemm g, const Sched& S, const Epi& E, const int tid_in) {
;     ...
;             const bool last = (t == nt - 2);
;             const char* a1 = cA + (size_t)(t + 1) * kstep;
;             const char* a2 = last ? nA : cA + (size_t)(t + 2) * kstep; const char* b2 = last ? nB : cB + (size_t)(t + 2) * kstep;
;             const char* a3 = a2 + kstep; const char* b3 = b2 + kstep;
;     ...
;             PG8_WAIT_V(8); PG8_WAIT_L(0); PG8_BAR; PG8_MMA(0, 0, At, B0); PG8_MMA(0, 1, At, B1); PG8_BAR; PG8_SCHED;
;             PG8_LDA(At, 1, 1); PG8_STAGE(PG8_SB(1, 0), b3, voffB); PG8_STAGE(PG8_SB(1, 1), b3 + hstep, voffB); PG8_STAGE(PG8_SA(1, 0), a3, voffA);
;             PG8_WAIT_V(8); PG8_WAIT_L(0); PG8_BAR; PG8_MMA(1, 0, At, B0); PG8_MMA(1, 1, At, B1); PG8_BAR; PG8_SCHED;
	s_setprio 1
	s_waitcnt lgkmcnt(0)
	v_mfma_f32_16x16x32_bf16 v[126:129], v[130:133], v[162:165], v[126:129]
	v_mfma_f32_16x16x32_bf16 v[122:125], v[138:141], v[162:165], v[122:125]
	v_mfma_f32_16x16x32_bf16 v[110:113], v[130:133], v[170:173], v[110:113]
	v_mfma_f32_16x16x32_bf16 v[106:109], v[138:141], v[170:173], v[106:109]
	v_mfma_f32_16x16x32_bf16 v[94:97], v[130:133], v[178:181], v[94:97]
	v_mfma_f32_16x16x32_bf16 v[90:93], v[138:141], v[178:181], v[90:93]
	v_mfma_f32_16x16x32_bf16 v[78:81], v[130:133], v[186:189], v[78:81]
	v_mfma_f32_16x16x32_bf16 v[74:77], v[138:141], v[186:189], v[74:77]
	v_mfma_f32_16x16x32_bf16 v[126:129], v[134:137], v[166:169], v[126:129]
	v_mfma_f32_16x16x32_bf16 v[122:125], v[142:145], v[166:169], v[122:125]
	v_mfma_f32_16x16x32_bf16 v[110:113], v[134:137], v[174:177], v[110:113]
	v_mfma_f32_16x16x32_bf16 v[106:109], v[142:145], v[174:177], v[106:109]
	v_mfma_f32_16x16x32_bf16 v[94:97], v[134:137], v[182:185], v[94:97]
	v_mfma_f32_16x16x32_bf16 v[90:93], v[142:145], v[182:185], v[90:93]
	v_mfma_f32_16x16x32_bf16 v[78:81], v[134:137], v[190:193], v[78:81]
	v_mfma_f32_16x16x32_bf16 v[74:77], v[142:145], v[190:193], v[74:77]
	s_setprio 0
	s_setprio 1
	v_mfma_f32_16x16x32_bf16 v[118:121], v[146:149], v[162:165], v[118:121]
	v_mfma_f32_16x16x32_bf16 v[114:117], v[154:157], v[162:165], v[114:117]
	v_mfma_f32_16x16x32_bf16 v[102:105], v[146:149], v[170:173], v[102:105]
	v_mfma_f32_16x16x32_bf16 v[98:101], v[154:157], v[170:173], v[98:101]
	v_mfma_f32_16x16x32_bf16 v[86:89], v[146:149], v[178:181], v[86:89]
	v_mfma_f32_16x16x32_bf16 v[82:85], v[154:157], v[178:181], v[82:85]
	v_mfma_f32_16x16x32_bf16 v[70:73], v[146:149], v[186:189], v[70:73]
	v_mfma_f32_16x16x32_bf16 v[66:69], v[154:157], v[186:189], v[66:69]
	v_mfma_f32_16x16x32_bf16 v[118:121], v[150:153], v[166:169], v[118:121]
	v_mfma_f32_16x16x32_bf16 v[114:117], v[158:161], v[166:169], v[114:117]
	v_mfma_f32_16x16x32_bf16 v[102:105], v[150:153], v[174:177], v[102:105]
	v_mfma_f32_16x16x32_bf16 v[98:101], v[158:161], v[174:177], v[98:101]
	v_mfma_f32_16x16x32_bf16 v[86:89], v[150:153], v[182:185], v[86:89]
	v_mfma_f32_16x16x32_bf16 v[82:85], v[158:161], v[182:185], v[82:85]
	v_mfma_f32_16x16x32_bf16 v[70:73], v[150:153], v[190:193], v[70:73]
	v_mfma_f32_16x16x32_bf16 v[66:69], v[158:161], v[190:193], v[66:69]
	s_setprio 0
	s_barrier
	s_add_i32 s26, s26, s16
	v_lshl_add_u64 v[194:195], v[194:195], 0, s[20:21]
	s_mov_b32 m0, s26
	ds_read_b128 v[162:165], v244 offset:49152
	ds_read_b128 v[166:169], v244 offset:50176
	ds_read_b128 v[170:173], v244 offset:51200
	ds_read_b128 v[174:177], v244 offset:52224
	ds_read_b128 v[178:181], v244 offset:53248
	ds_read_b128 v[182:185], v244 offset:54272
	ds_read_b128 v[186:189], v244 offset:55296
	ds_read_b128 v[190:193], v244 offset:56320
	global_load_lds_dwordx4 v[194:195], off
	v_lshl_add_u64 v[194:195], v[196:197], 0, s[20:21]
	s_add_i32 m0, s26, 0x2000
	s_add_i32 s26, s51, s16
	global_load_lds_dwordx4 v[194:195], off
	v_lshl_add_u64 v[194:195], v[198:199], 0, s[20:21]
	s_mov_b32 m0, s26
	s_nop 0
	global_load_lds_dwordx4 v[194:195], off
	v_lshl_add_u64 v[194:195], v[200:201], 0, s[20:21]
	s_add_i32 m0, s26, 0x2000
	s_nop 0
	global_load_lds_dwordx4 v[194:195], off
	v_lshl_add_u64 v[194:195], v[202:203], 0, s[20:21]
	s_mov_b32 m0, s1
	s_nop 0
	global_load_lds_dwordx4 v[194:195], off
	v_lshl_add_u64 v[194:195], v[204:205], 0, s[20:21]
	s_mov_b32 m0, s8
	s_nop 0
	global_load_lds_dwordx4 v[194:195], off
	s_waitcnt vmcnt(8)
	s_waitcnt lgkmcnt(0)
	s_barrier
	s_setprio 1
	s_waitcnt lgkmcnt(0)
	v_mfma_f32_16x16x32_bf16 v[62:65], v[130:133], v[162:165], v[62:65]
	v_mfma_f32_16x16x32_bf16 v[58:61], v[138:141], v[162:165], v[58:61]
	v_mfma_f32_16x16x32_bf16 v[46:49], v[130:133], v[170:173], v[46:49]
	v_mfma_f32_16x16x32_bf16 v[42:45], v[138:141], v[170:173], v[42:45]
	v_mfma_f32_16x16x32_bf16 v[30:33], v[130:133], v[178:181], v[30:33]
	v_mfma_f32_16x16x32_bf16 v[26:29], v[138:141], v[178:181], v[26:29]
	v_mfma_f32_16x16x32_bf16 v[14:17], v[130:133], v[186:189], v[14:17]
	v_mfma_f32_16x16x32_bf16 v[10:13], v[138:141], v[186:189], v[10:13]
	v_mfma_f32_16x16x32_bf16 v[62:65], v[134:137], v[166:169], v[62:65]
	v_mfma_f32_16x16x32_bf16 v[58:61], v[142:145], v[166:169], v[58:61]
	v_mfma_f32_16x16x32_bf16 v[46:49], v[134:137], v[174:177], v[46:49]
	v_mfma_f32_16x16x32_bf16 v[42:45], v[142:145], v[174:177], v[42:45]
	v_mfma_f32_16x16x32_bf16 v[30:33], v[134:137], v[182:185], v[30:33]
	v_mfma_f32_16x16x32_bf16 v[26:29], v[142:145], v[182:185], v[26:29]
	v_mfma_f32_16x16x32_bf16 v[14:17], v[134:137], v[190:193], v[14:17]
	s_add_u32 vcc_lo, vcc_lo, 0x100
	v_mfma_f32_16x16x32_bf16 v[10:13], v[142:145], v[190:193], v[10:13]
	s_addc_u32 vcc_hi, vcc_hi, 0
	s_setprio 0
	s_setprio 1
	v_mfma_f32_16x16x32_bf16 v[54:57], v[146:149], v[162:165], v[54:57]
	s_add_u32 s46, s46, 0x100
	v_mfma_f32_16x16x32_bf16 v[50:53], v[154:157], v[162:165], v[50:53]
	s_addc_u32 s47, s47, 0
	v_mfma_f32_16x16x32_bf16 v[38:41], v[146:149], v[170:173], v[38:41]
	s_mov_b32 s48, s50
	v_mfma_f32_16x16x32_bf16 v[34:37], v[154:157], v[170:173], v[34:37]
	s_add_i32 s50, s48, 2
	v_mfma_f32_16x16x32_bf16 v[22:25], v[146:149], v[178:181], v[22:25]
	s_add_u32 s51, s46, 0x80
	v_mfma_f32_16x16x32_bf16 v[18:21], v[154:157], v[178:181], v[18:21]
	s_addc_u32 s49, s47, 0
	v_mfma_f32_16x16x32_bf16 v[6:9], v[146:149], v[186:189], v[6:9]
	s_add_i32 s26, 0, 0x10000
	v_mfma_f32_16x16x32_bf16 v[2:5], v[154:157], v[186:189], v[2:5]
	s_cmp_eq_u32 s9, s48
	v_mfma_f32_16x16x32_bf16 v[54:57], v[150:153], v[166:169], v[54:57]
	s_cselect_b32 s49, s83, s49
	v_mfma_f32_16x16x32_bf16 v[50:53], v[158:161], v[166:169], v[50:53]
	s_cselect_b32 s48, s82, s51
	v_mfma_f32_16x16x32_bf16 v[38:41], v[150:153], v[174:177], v[38:41]
	s_cselect_b32 s61, s85, vcc_hi
	v_mfma_f32_16x16x32_bf16 v[34:37], v[158:161], v[174:177], v[34:37]
	s_cselect_b32 s60, s84, vcc_lo
	v_mfma_f32_16x16x32_bf16 v[22:25], v[150:153], v[182:185], v[22:25]
	s_add_i32 s51, 0, 0x14000
	v_mfma_f32_16x16x32_bf16 v[18:21], v[158:161], v[182:185], v[18:21]
	s_add_i32 m0, s50, -2
	v_mfma_f32_16x16x32_bf16 v[6:9], v[150:153], v[190:193], v[6:9]
	s_cmp_ge_u32 m0, s27
	v_mfma_f32_16x16x32_bf16 v[2:5], v[158:161], v[190:193], v[2:5]
	s_setprio 0
	s_barrier
	s_cbranch_scc0 .LBB0_226
	s_and_b64 vcc, exec, s[76:77]
	s_cbranch_vccz .LBB0_229
	s_barrier
